# v31 + P2 queue loop: waves 4-7 touch one 128 KiB chunk of the XCD's x_prompt region per popped item (items >= 32) so that P3's residual reads hit the LLC
# baseline (speedup 1.0000x reference)
.LBB0_396:
	v_readlane_b32 s4, v251, 6
	v_readlane_b32 s12, v251, 14
	v_readlane_b32 s13, v251, 15
	v_readlane_b32 s14, v251, 16
	v_readlane_b32 s15, v251, 17
	v_readlane_b32 s16, v251, 18
	v_readlane_b32 s17, v251, 19
	v_readlane_b32 s18, v251, 20
	v_readlane_b32 s19, v251, 21
	s_mov_b64 s[12:13], s[16:17]
	s_lshl_b32 s2, s38, 6
	s_lshl_b32 s0, s38, 8
	s_mov_b64 s[14:15], s[18:19]
	s_add_u32 s0, s14, s0
	s_addc_u32 s1, s15, 0
	s_add_u32 s0, s0, 0x10000
	s_addc_u32 s1, s1, 0
	v_and_b32_e32 v3, 0x7c, v152
	v_readlane_b32 s5, v251, 7
	v_readlane_b32 s6, v251, 8
	v_readlane_b32 s7, v251, 9
	v_readlane_b32 s8, v251, 10
	v_readlane_b32 s9, v251, 11
	v_readlane_b32 s10, v251, 12
	v_readlane_b32 s11, v251, 13
	v_writelane_b32 v251, s0, 43
	v_lshlrev_b32_e32 v192, 1, v3
	v_mov_b32_e32 v193, 0
	v_writelane_b32 v251, s1, 44
	s_add_i32 s0, s2, 0xffffff80
	v_lshl_add_u64 v[194:195], s[26:27], 0, v[192:193]
	v_lshlrev_b32_e32 v192, 1, v151
	v_writelane_b32 v251, s0, 53
	v_lshl_add_u64 v[4:5], s[14:15], 0, v[192:193]
	s_mov_b64 s[0:1], 0x1d00000
	v_writelane_b32 v250, s68, 14
	v_lshl_add_u64 v[196:197], v[4:5], 0, s[0:1]
	s_lshl_b32 s0, s38, 11
	s_lshl_b32 s3, s38, 21
	v_writelane_b32 v250, s0, 3
	s_add_u32 s0, s22, s3
	v_readlane_b32 s4, v251, 22
	s_addc_u32 s1, s23, 0
	v_readlane_b32 s6, v251, 24
	v_readlane_b32 s7, v251, 25
	v_readlane_b32 s10, v251, 28
	v_readlane_b32 s11, v251, 29
	v_readlane_b32 s14, v251, 32
	v_readlane_b32 s15, v251, 33
	s_add_u32 s3, s24, s3
	v_lshlrev_b32_e32 v192, 2, v3
	s_mov_b64 s[14:15], s[10:11]
	s_mov_b64 s[10:11], s[6:7]
	v_writelane_b32 v250, s3, 4
	s_addc_u32 s3, s25, 0
	v_lshl_add_u64 v[198:199], s[10:11], 0, v[192:193]
	v_lshlrev_b32_e32 v192, 10, v190
	s_cmp_lg_u32 0, -1
	v_lshl_add_u64 v[200:201], s[0:1], 0, v[192:193]
	v_lshlrev_b32_e32 v6, 1, v0
	s_cselect_b32 s0, 0, 0
	v_lshrrev_b32_e32 v8, 5, v190
	v_lshlrev_b32_e32 v10, 3, v0
	v_and_b32_e32 v6, 32, v6
	s_addk_i32 s0, 0x6000
	v_and_b32_e32 v12, 0xc0, v147
	v_lshrrev_b32_e32 v225, 6, v0
	v_and_b32_e32 v4, 24, v10
	v_add_u32_e32 v7, s0, v6
	v_lshl_or_b32 v12, v8, 8, v12
	v_add_u32_e32 v6, 0, v6
	v_add3_u32 v229, v6, v4, v12
	v_lshlrev_b32_e32 v6, 12, v225
	v_readlane_b32 s0, v251, 51
	v_add3_u32 v227, v7, v4, v12
	v_lshlrev_b32_e32 v7, 10, v8
	v_lshlrev_b32_e32 v13, 4, v222
	v_lshl_or_b32 v192, s38, 15, v6
	v_readlane_b32 s1, v251, 52
	v_add3_u32 v228, 0, v7, v13
	v_readlane_b32 s5, v251, 23
	v_lshl_add_u64 v[6:7], s[0:1], 0, v[192:193]
	v_lshlrev_b32_e32 v192, 2, v190
	s_add_i32 s0, 0, 0x14800
	v_lshl_add_u64 v[202:203], v[6:7], 0, v[192:193]
	v_lshl_add_u32 v230, v0, 2, s0
	v_lshlrev_b32_e32 v6, 9, v222
	v_add_u32_e32 v231, s0, v146
	v_cmp_gt_u32_e64 s[0:1], 32, v190
	v_lshrrev_b32_e32 v7, 3, v190
	v_readlane_b32 s8, v251, 26
	v_readlane_b32 s9, v251, 27
	v_readlane_b32 s12, v251, 30
	v_readlane_b32 s13, v251, 31
	v_readlane_b32 s16, v251, 34
	v_readlane_b32 s17, v251, 35
	v_readlane_b32 s18, v251, 36
	v_readlane_b32 s19, v251, 37
	v_lshl_or_b32 v6, v8, 3, v6
	v_lshlrev_b32_e32 v232, 2, v8
	v_writelane_b32 v251, s0, 51
	v_lshlrev_b32_e32 v233, 9, v8
	v_and_b32_e32 v8, 56, v10
	v_lshlrev_b32_e32 v234, 7, v7
	v_lshlrev_b32_e32 v10, 10, v7
	v_or_b32_e32 v12, 8, v7
	v_or_b32_e32 v13, 16, v7
	v_or_b32_e32 v7, 24, v7
	v_lshlrev_b32_e32 v2, 2, v150
	v_lshl_add_u32 v5, v149, 4, 0
	v_mul_u32_u24_e32 v3, 0x110, v3
	v_add_u32_e32 v9, 0, v148
	v_mul_u32_u24_e32 v11, 0x110, v223
	v_writelane_b32 v250, s3, 6
	v_writelane_b32 v251, s1, 52
	v_lshlrev_b32_e32 v235, 7, v12
	v_lshlrev_b32_e32 v12, 10, v12
	v_lshlrev_b32_e32 v14, 10, v13
	v_lshlrev_b32_e32 v237, 7, v7
	v_lshlrev_b32_e32 v16, 10, v7
	s_add_i32 s0, s2, 0xffffff7f
	v_sub_u32_e32 v7, v222, v232
	s_add_i32 s12, 0, 0x22800
	s_mov_b32 s85, 0
	v_lshlrev_b32_e32 v224, 12, v149
	v_lshrrev_b32_e32 v226, 2, v190
	v_lshlrev_b32_e32 v236, 7, v13
	v_writelane_b32 v250, s0, 8
	v_add_u32_e32 v238, 0xffffff80, v7
	s_mov_b32 s87, 0xffff0000
	v_mov_b32_e32 v239, 0x358637bd
	s_mov_b32 s68, 0xf800000
	v_mov_b32_e32 v240, 0x260
	s_movk_i32 s69, 0x7fff
	v_add_u32_e32 v241, v5, v3
	v_lshlrev_b32_e32 v204, 1, v4
	v_lshlrev_b32_e32 v242, 1, v6
	s_mov_b32 s0, 0x41000000
	v_lshlrev_b32_e32 v206, 1, v8
	v_lshlrev_b32_e32 v208, 1, v10
	v_lshlrev_b32_e32 v210, 1, v12
	v_lshlrev_b32_e32 v212, 1, v14
	v_lshlrev_b32_e32 v214, 1, v16
	v_mov_b32_e32 v243, s12
	v_lshlrev_b32_e32 v216, 1, v2
	v_add_u32_e32 v244, v9, v11
	v_mov_b32_e32 v245, 1
	v_mov_b32_e32 v246, 0xff800000
	s_waitcnt vmcnt(0) lgkmcnt(0)
	s_barrier
	v_writelane_b32 v250, s12, 15
	s_mov_b32 s101, -1
	s_branch .LBB0_400

.LBB0_400:
	v_readfirstlane_b32 s98, v0
	s_cmp_lt_u32 s98, 256
	s_cbranch_scc1 .Lmy_x2_skip
	s_cmp_lt_i32 s101, 32
	s_cbranch_scc1 .Lmy_x2_skip
	v_readlane_b32 s98, v251, 63
	s_and_b32 s98, s98, 7
	s_lshl_b32 s98, s98, 23
	s_sub_i32 s99, s101, 32
	s_lshl_b32 s99, s99, 17
	s_add_u32 s98, s98, s99
	s_add_u32 s98, s76, s98
	s_addc_u32 s99, s77, 0
	v_add_u32_e32 v252, 0xffffff00, v0
	v_lshlrev_b32_e32 v252, 7, v252
	s_nop 1
	global_load_dword v255, v252, s[98:99]
	v_add_u32_e32 v253, 0x8000, v252
	global_load_dword v255, v253, s[98:99]
	v_add_u32_e32 v253, 0x10000, v252
	global_load_dword v255, v253, s[98:99]
	v_add_u32_e32 v253, 0x18000, v252
	global_load_dword v255, v253, s[98:99]

.LBB0_404:
	s_or_b64 exec, exec, s[2:3]
	s_waitcnt lgkmcnt(0)
	s_barrier
	ds_read_b32 v2, v243
	s_movk_i32 s1, 0x5f
	s_mov_b64 s[2:3], -1
	s_waitcnt lgkmcnt(0)
	s_barrier
	v_cmp_lt_i32_e32 vcc, s1, v2
	v_readfirstlane_b32 s8, v2
	s_mov_b32 s101, s8
	s_cbranch_vccnz .LBB0_399
	s_cmp_gt_i32 s8, 63
	s_cbranch_scc0 .LBB0_415
	s_lshl_b32 s2, s8, 1
	v_readlane_b32 s1, v251, 53
	s_add_i32 s1, s1, s2
	v_readlane_b32 s3, v250, 8
	s_add_i32 s2, s3, s2
	s_lshl_b32 s3, s1, 5
	s_lshl_b32 s9, s1, 7
	s_branch .LBB0_408
